# every MFMA run of the three GEMM K-loops padded onto an 8-byte instruction boundary (6 s_nop), on top of the placement-matched NA specialization
# baseline (speedup 1.0000x reference)
; #define PG8_STAGE(bufoff, gbase, voff) do { _Pragma("unroll") for (int _i = 0; _i < 2; ++_i) \
;         __builtin_amdgcn_global_load_lds((const unsigned*)((const char*)(gbase) + (voff)[_i]), (PG8_LAS unsigned*)(lds + (bufoff) + ldsw + _i * 8192), 16, 0, 0); } while (0)
; #define PG8_LDA(dst, b, h) do { _Pragma("unroll") for (int m = 0; m < 4; ++m) _Pragma("unroll") for (int k = 0; k < 2; ++k) dst[m][k] = *(const PG8_LAS bf16x8*)(lds + PG8_SA(b, h) + aoff + m * 2048 + k * 1024); } while (0)
; #define PG8_LDB(dst, b, h) do { _Pragma("unroll") for (int n = 0; n < 2; ++n) _Pragma("unroll") for (int k = 0; k < 2; ++k) dst[n][k] = *(const PG8_LAS bf16x8*)(lds + PG8_SB(b, h) + boff + n * 2048 + k * 1024); } while (0)
; #define PG8_MMA(ai, bj, At, Bt) do { __builtin_amdgcn_s_setprio(1); _Pragma("unroll") for (int m = 0; m < 4; ++m) _Pragma("unroll") for (int n = 0; n < 2; ++n) _Pragma("unroll") for (int k = 0; k < 2; ++k) \
;         acc[ai][bj][m][n] = __builtin_amdgcn_mfma_f32_16x16x32_bf16(Bt[n][k], At[m][k], acc[ai][bj][m][n], 0, 0, 0); __builtin_amdgcn_s_setprio(0); } while (0)
; #define PG8_WAIT_V(n) asm volatile("s_waitcnt vmcnt(" #n ")" ::: "memory")
; #define PG8_BAR __builtin_amdgcn_s_barrier()
; template <class Epi, class Sched, bool ALIGN_EPI = false, bool SP2 = false>
; __device__ __forceinline__ void gemm_phase(PG8_LAS unsigned char* lds, const Gemm g, const Sched& S, const Epi& E, const int tid_in) {
;     ...
;         for (int t = 0; t < nt; t += 2) {
;             const bool last = (t == nt - 2);
;             const char* a1 = cA + (size_t)(t + 1) * kstep;
;             const char* a2 = last ? nA : cA + (size_t)(t + 2) * kstep; const char* b2 = last ? nB : cB + (size_t)(t + 2) * kstep;
;             const char* a3 = a2 + kstep; const char* b3 = b2 + kstep;
;             if (last && has_next) S.a_ready(nxt);
;             if constexpr (SP2) {
;             PG8_LDB(B0, 0, 0); PG8_LDB(B1, 0, 1); PG8_SCHED; PG8_LDA(At, 0, 0); PG8_STAGE(PG8_SA(1, 1), a1 + hstep, voffA);
;             PG8_WAIT_V(8); PG8_WAIT_L(0); PG8_BAR; PG8_MMA(0, 0, At, B0); PG8_MMA(0, 1, At, B1); PG8_BAR; PG8_SCHED;
;             PG8_LDA(At, 0, 1); PG8_STAGE(PG8_SB(0, 0), b2, voffB); PG8_STAGE(PG8_SB(0, 1), b2 + hstep, voffB); PG8_STAGE(PG8_SA(0, 0), a2, voffA);
;             PG8_WAIT_V(8); PG8_WAIT_L(0); PG8_BAR; PG8_MMA(1, 0, At, B0); PG8_MMA(1, 1, At, B1); PG8_BAR; PG8_SCHED;
.LBB0_42:
	s_add_u32 s10, s4, 0xfffc0080
	s_addc_u32 s11, s5, -1
	s_add_i32 s61, 0, 0x10000
	s_cmp_eq_u32 s60, 12
	s_cselect_b32 s13, s14, s11
	s_cselect_b32 s12, s15, s10
	s_cselect_b32 s11, s23, s59
	s_cselect_b32 s10, s25, s58
	s_add_i32 s64, 0, 0x14000
	s_waitcnt vmcnt(0)
	v_add_u32_e32 v76, s61, v162
	v_add_u32_e32 v160, s64, v162
	ds_read_b128 v[56:59], v76
	ds_read_b128 v[64:67], v76 offset:1024
	ds_read_b128 v[68:71], v76 offset:2048
	ds_read_b128 v[76:79], v76 offset:3072
	ds_read_b128 v[170:173], v160
	ds_read_b128 v[174:177], v160 offset:1024
	ds_read_b128 v[178:181], v160 offset:2048
	ds_read_b128 v[182:185], v160 offset:3072
	v_lshl_add_u64 v[160:161], s[4:5], 0, v[156:157]
	s_add_i32 m0, s48, 0xc000
	ds_read_b128 v[186:189], v168
	ds_read_b128 v[200:203], v168 offset:1024
	ds_read_b128 v[204:207], v168 offset:2048
	ds_read_b128 v[208:211], v168 offset:3072
	ds_read_b128 v[212:215], v168 offset:4096
	ds_read_b128 v[234:237], v168 offset:5120
	ds_read_b128 v[238:241], v168 offset:6144
	ds_read_b128 v[242:245], v168 offset:7168
	global_load_lds_dwordx4 v[160:161], off
	v_lshl_add_u64 v[160:161], s[4:5], 0, v[158:159]
	s_add_i32 m0, s48, 0xe000
	s_nop 0
	global_load_lds_dwordx4 v[160:161], off
	s_waitcnt vmcnt(8)
	s_waitcnt lgkmcnt(0)
	s_barrier
	s_setprio 1
	s_waitcnt lgkmcnt(0)
	s_nop 0
	v_mfma_f32_16x16x32_bf16 v[140:143], v[56:59], v[186:189], v[140:143]
	v_mfma_f32_16x16x32_bf16 v[136:139], v[68:71], v[186:189], v[136:139]
	v_mfma_f32_16x16x32_bf16 v[124:127], v[56:59], v[204:207], v[124:127]
	v_mfma_f32_16x16x32_bf16 v[120:123], v[68:71], v[204:207], v[120:123]
	v_mfma_f32_16x16x32_bf16 v[108:111], v[56:59], v[212:215], v[108:111]
	v_mfma_f32_16x16x32_bf16 v[104:107], v[68:71], v[212:215], v[104:107]
	v_mfma_f32_16x16x32_bf16 v[92:95], v[56:59], v[238:241], v[92:95]
	v_mfma_f32_16x16x32_bf16 v[88:91], v[68:71], v[238:241], v[88:91]
	v_mfma_f32_16x16x32_bf16 v[140:143], v[64:67], v[200:203], v[140:143]
	v_mfma_f32_16x16x32_bf16 v[136:139], v[76:79], v[200:203], v[136:139]
	v_mfma_f32_16x16x32_bf16 v[124:127], v[64:67], v[208:211], v[124:127]
	v_mfma_f32_16x16x32_bf16 v[120:123], v[76:79], v[208:211], v[120:123]
	v_mfma_f32_16x16x32_bf16 v[108:111], v[64:67], v[234:237], v[108:111]
	v_mfma_f32_16x16x32_bf16 v[104:107], v[76:79], v[234:237], v[104:107]
	v_mfma_f32_16x16x32_bf16 v[92:95], v[64:67], v[242:245], v[92:95]
	v_mfma_f32_16x16x32_bf16 v[88:91], v[76:79], v[242:245], v[88:91]
	s_setprio 0
	s_setprio 1
	v_mfma_f32_16x16x32_bf16 v[132:135], v[170:173], v[186:189], v[132:135]
	v_mfma_f32_16x16x32_bf16 v[128:131], v[178:181], v[186:189], v[128:131]
	v_mfma_f32_16x16x32_bf16 v[116:119], v[170:173], v[204:207], v[116:119]
	v_mfma_f32_16x16x32_bf16 v[112:115], v[178:181], v[204:207], v[112:115]
	v_mfma_f32_16x16x32_bf16 v[100:103], v[170:173], v[212:215], v[100:103]
	v_mfma_f32_16x16x32_bf16 v[96:99], v[178:181], v[212:215], v[96:99]
	v_mfma_f32_16x16x32_bf16 v[84:87], v[170:173], v[238:241], v[84:87]
	v_mfma_f32_16x16x32_bf16 v[80:83], v[178:181], v[238:241], v[80:83]
	v_mfma_f32_16x16x32_bf16 v[132:135], v[174:177], v[200:203], v[132:135]
	v_mfma_f32_16x16x32_bf16 v[128:131], v[182:185], v[200:203], v[128:131]
	v_mfma_f32_16x16x32_bf16 v[116:119], v[174:177], v[208:211], v[116:119]
	v_mfma_f32_16x16x32_bf16 v[112:115], v[182:185], v[208:211], v[112:115]
	v_mfma_f32_16x16x32_bf16 v[100:103], v[174:177], v[234:237], v[100:103]
	v_mfma_f32_16x16x32_bf16 v[96:99], v[182:185], v[234:237], v[96:99]
	v_mfma_f32_16x16x32_bf16 v[84:87], v[174:177], v[242:245], v[84:87]
	v_mfma_f32_16x16x32_bf16 v[80:83], v[182:185], v[242:245], v[80:83]
	s_setprio 0
	s_barrier
	s_add_i32 s61, s61, s41
	v_lshl_add_u64 v[160:161], s[10:11], 0, v[148:149]
	s_mov_b32 m0, s61
	ds_read_b128 v[186:189], v168 offset:16384
	ds_read_b128 v[200:203], v168 offset:17408
	ds_read_b128 v[204:207], v168 offset:18432
	ds_read_b128 v[208:211], v168 offset:19456
	ds_read_b128 v[212:215], v168 offset:20480
	ds_read_b128 v[234:237], v168 offset:21504
	ds_read_b128 v[238:241], v168 offset:22528
	ds_read_b128 v[242:245], v168 offset:23552
	global_load_lds_dwordx4 v[160:161], off
	s_add_i32 m0, s61, 0x2000
	s_add_u32 s62, s10, 0x40000
	v_lshl_add_u64 v[190:191], s[10:11], 0, v[144:145]
	s_addc_u32 s63, s11, 0
	s_add_i32 s61, s64, s41
	global_load_lds_dwordx4 v[190:191], off
	v_lshl_add_u64 v[218:219], s[62:63], 0, v[148:149]
	s_mov_b32 m0, s61
	v_lshl_add_u64 v[220:221], s[12:13], 0, v[146:147]
	global_load_lds_dwordx4 v[218:219], off
	v_lshl_add_u64 v[218:219], s[62:63], 0, v[144:145]
	s_add_i32 m0, s61, 0x2000
	s_nop 0
	global_load_lds_dwordx4 v[218:219], off
	v_lshl_add_u64 v[218:219], s[12:13], 0, v[150:151]
	s_mov_b32 m0, s48
	s_nop 0
	global_load_lds_dwordx4 v[218:219], off
	s_mov_b32 m0, s49
	s_nop 0
	global_load_lds_dwordx4 v[220:221], off
	s_waitcnt vmcnt(8)
	s_waitcnt lgkmcnt(0)
	s_barrier
; #define PG8_STAGE(bufoff, gbase, voff) do { _Pragma("unroll") for (int _i = 0; _i < 2; ++_i) \
;         __builtin_amdgcn_global_load_lds((const unsigned*)((const char*)(gbase) + (voff)[_i]), (PG8_LAS unsigned*)(lds + (bufoff) + ldsw + _i * 8192), 16, 0, 0); } while (0)
; #define PG8_LDA(dst, b, h) do { _Pragma("unroll") for (int m = 0; m < 4; ++m) _Pragma("unroll") for (int k = 0; k < 2; ++k) dst[m][k] = *(const PG8_LAS bf16x8*)(lds + PG8_SA(b, h) + aoff + m * 2048 + k * 1024); } while (0)
; #define PG8_LDB(dst, b, h) do { _Pragma("unroll") for (int n = 0; n < 2; ++n) _Pragma("unroll") for (int k = 0; k < 2; ++k) dst[n][k] = *(const PG8_LAS bf16x8*)(lds + PG8_SB(b, h) + boff + n * 2048 + k * 1024); } while (0)
; #define PG8_MMA(ai, bj, At, Bt) do { __builtin_amdgcn_s_setprio(1); _Pragma("unroll") for (int m = 0; m < 4; ++m) _Pragma("unroll") for (int n = 0; n < 2; ++n) _Pragma("unroll") for (int k = 0; k < 2; ++k) \
;         acc[ai][bj][m][n] = __builtin_amdgcn_mfma_f32_16x16x32_bf16(Bt[n][k], At[m][k], acc[ai][bj][m][n], 0, 0, 0); __builtin_amdgcn_s_setprio(0); } while (0)
; #define PG8_WAIT_V(n) asm volatile("s_waitcnt vmcnt(" #n ")" ::: "memory")
; #define PG8_WAIT_L(n) asm volatile("s_waitcnt lgkmcnt(" #n ")" ::: "memory")
; #define PG8_BAR __builtin_amdgcn_s_barrier()
; #define PG8_SCHED __builtin_amdgcn_sched_barrier(0)
; template <class Epi, class Sched, bool ALIGN_EPI = false, bool SP2 = false>
; __device__ __forceinline__ void gemm_phase(PG8_LAS unsigned char* lds, const Gemm g, const Sched& S, const Epi& E, const int tid_in) {
;     ...
;             PG8_WAIT_V(8); PG8_WAIT_L(0); PG8_BAR; PG8_MMA(1, 0, At, B0); PG8_MMA(1, 1, At, B1); PG8_BAR; PG8_SCHED;
;             PG8_LDB(B0, 1, 0); PG8_LDB(B1, 1, 1); PG8_SCHED; PG8_LDA(At, 1, 0); PG8_STAGE(PG8_SA(0, 1), a2 + hstep, voffA);
;             PG8_WAIT_V(8); PG8_WAIT_L(0); PG8_BAR; PG8_MMA(0, 0, At, B0); PG8_MMA(0, 1, At, B1); PG8_BAR; PG8_SCHED;
;             PG8_LDA(At, 1, 1); PG8_STAGE(PG8_SB(1, 0), b3, voffB); PG8_STAGE(PG8_SB(1, 1), b3 + hstep, voffB); PG8_STAGE(PG8_SA(1, 0), a3, voffA);
;             PG8_WAIT_V(8); PG8_WAIT_L(0); PG8_BAR; PG8_MMA(1, 0, At, B0); PG8_MMA(1, 1, At, B1); PG8_BAR; PG8_SCHED;
	s_setprio 1
	s_waitcnt lgkmcnt(0)
	s_nop 0
	v_mfma_f32_16x16x32_bf16 v[72:75], v[56:59], v[186:189], v[72:75]
	v_mfma_f32_16x16x32_bf16 v[60:63], v[68:71], v[186:189], v[60:63]
	v_mfma_f32_16x16x32_bf16 v[44:47], v[56:59], v[204:207], v[44:47]
	v_mfma_f32_16x16x32_bf16 v[40:43], v[68:71], v[204:207], v[40:43]
	v_mfma_f32_16x16x32_bf16 v[28:31], v[56:59], v[212:215], v[28:31]
	v_mfma_f32_16x16x32_bf16 v[24:27], v[68:71], v[212:215], v[24:27]
	v_mfma_f32_16x16x32_bf16 v[12:15], v[56:59], v[238:241], v[12:15]
	v_mfma_f32_16x16x32_bf16 v[8:11], v[68:71], v[238:241], v[8:11]
	v_mfma_f32_16x16x32_bf16 v[72:75], v[64:67], v[200:203], v[72:75]
	v_mfma_f32_16x16x32_bf16 v[60:63], v[76:79], v[200:203], v[60:63]
	v_mfma_f32_16x16x32_bf16 v[44:47], v[64:67], v[208:211], v[44:47]
	v_mfma_f32_16x16x32_bf16 v[40:43], v[76:79], v[208:211], v[40:43]
	v_mfma_f32_16x16x32_bf16 v[28:31], v[64:67], v[234:237], v[28:31]
	v_mfma_f32_16x16x32_bf16 v[24:27], v[76:79], v[234:237], v[24:27]
	v_mfma_f32_16x16x32_bf16 v[12:15], v[64:67], v[242:245], v[12:15]
	v_mfma_f32_16x16x32_bf16 v[8:11], v[76:79], v[242:245], v[8:11]
	s_setprio 0
	s_setprio 1
	v_mfma_f32_16x16x32_bf16 v[52:55], v[170:173], v[186:189], v[52:55]
	v_mfma_f32_16x16x32_bf16 v[48:51], v[178:181], v[186:189], v[48:51]
	v_mfma_f32_16x16x32_bf16 v[36:39], v[170:173], v[204:207], v[36:39]
	v_mfma_f32_16x16x32_bf16 v[32:35], v[178:181], v[204:207], v[32:35]
	v_mfma_f32_16x16x32_bf16 v[20:23], v[170:173], v[212:215], v[20:23]
	v_mfma_f32_16x16x32_bf16 v[16:19], v[178:181], v[212:215], v[16:19]
	v_mfma_f32_16x16x32_bf16 v[4:7], v[170:173], v[238:241], v[4:7]
	v_mfma_f32_16x16x32_bf16 v[0:3], v[178:181], v[238:241], v[0:3]
	v_mfma_f32_16x16x32_bf16 v[52:55], v[174:177], v[200:203], v[52:55]
	v_mfma_f32_16x16x32_bf16 v[48:51], v[182:185], v[200:203], v[48:51]
	v_mfma_f32_16x16x32_bf16 v[36:39], v[174:177], v[208:211], v[36:39]
	v_mfma_f32_16x16x32_bf16 v[32:35], v[182:185], v[208:211], v[32:35]
	v_mfma_f32_16x16x32_bf16 v[20:23], v[174:177], v[234:237], v[20:23]
	v_mfma_f32_16x16x32_bf16 v[16:19], v[182:185], v[234:237], v[16:19]
	v_mfma_f32_16x16x32_bf16 v[4:7], v[174:177], v[242:245], v[4:7]
	v_mfma_f32_16x16x32_bf16 v[0:3], v[182:185], v[242:245], v[0:3]
	s_setprio 0
	s_barrier
	s_add_i32 s61, 0, 0x18000
	s_add_i32 s62, 0, 0x1c000
	v_add_u32_e32 v76, s61, v162
	v_add_u32_e32 v169, s62, v162
	ds_read_b128 v[56:59], v76
	ds_read_b128 v[64:67], v76 offset:1024
	ds_read_b128 v[68:71], v76 offset:2048
	ds_read_b128 v[76:79], v76 offset:3072
	ds_read_b128 v[170:173], v169
	ds_read_b128 v[174:177], v169 offset:1024
	ds_read_b128 v[178:181], v169 offset:2048
	ds_read_b128 v[182:185], v169 offset:3072
	s_add_u32 s12, s12, 0x40000
	s_addc_u32 s13, s13, 0
	s_mov_b32 m0, s50
	v_lshl_add_u64 v[230:231], s[12:13], 0, v[150:151]
	ds_read_b128 v[186:189], v168 offset:32768
	ds_read_b128 v[200:203], v168 offset:33792
	ds_read_b128 v[204:207], v168 offset:34816
	ds_read_b128 v[208:211], v168 offset:35840
	ds_read_b128 v[212:215], v168 offset:36864
	ds_read_b128 v[234:237], v168 offset:37888
	ds_read_b128 v[238:241], v168 offset:38912
	ds_read_b128 v[242:245], v168 offset:39936
	global_load_lds_dwordx4 v[230:231], off
	v_lshl_add_u64 v[230:231], s[12:13], 0, v[146:147]
	s_mov_b32 m0, s51
	s_nop 0
	global_load_lds_dwordx4 v[230:231], off
	s_waitcnt vmcnt(8)
	s_waitcnt lgkmcnt(0)
	s_barrier
	s_setprio 1
	s_waitcnt lgkmcnt(0)
	s_nop 0
	v_mfma_f32_16x16x32_bf16 v[140:143], v[56:59], v[186:189], v[140:143]
	v_mfma_f32_16x16x32_bf16 v[136:139], v[68:71], v[186:189], v[136:139]
	v_mfma_f32_16x16x32_bf16 v[124:127], v[56:59], v[204:207], v[124:127]
	v_mfma_f32_16x16x32_bf16 v[120:123], v[68:71], v[204:207], v[120:123]
	v_mfma_f32_16x16x32_bf16 v[108:111], v[56:59], v[212:215], v[108:111]
	v_mfma_f32_16x16x32_bf16 v[104:107], v[68:71], v[212:215], v[104:107]
	v_mfma_f32_16x16x32_bf16 v[92:95], v[56:59], v[238:241], v[92:95]
	v_mfma_f32_16x16x32_bf16 v[88:91], v[68:71], v[238:241], v[88:91]
	v_mfma_f32_16x16x32_bf16 v[140:143], v[64:67], v[200:203], v[140:143]
	v_mfma_f32_16x16x32_bf16 v[136:139], v[76:79], v[200:203], v[136:139]
	v_mfma_f32_16x16x32_bf16 v[124:127], v[64:67], v[208:211], v[124:127]
	v_mfma_f32_16x16x32_bf16 v[120:123], v[76:79], v[208:211], v[120:123]
	v_mfma_f32_16x16x32_bf16 v[108:111], v[64:67], v[234:237], v[108:111]
	v_mfma_f32_16x16x32_bf16 v[104:107], v[76:79], v[234:237], v[104:107]
	v_mfma_f32_16x16x32_bf16 v[92:95], v[64:67], v[242:245], v[92:95]
	v_mfma_f32_16x16x32_bf16 v[88:91], v[76:79], v[242:245], v[88:91]
	s_setprio 0
	s_setprio 1
	v_mfma_f32_16x16x32_bf16 v[132:135], v[170:173], v[186:189], v[132:135]
	v_mfma_f32_16x16x32_bf16 v[128:131], v[178:181], v[186:189], v[128:131]
	v_mfma_f32_16x16x32_bf16 v[116:119], v[170:173], v[204:207], v[116:119]
	v_mfma_f32_16x16x32_bf16 v[112:115], v[178:181], v[204:207], v[112:115]
	v_mfma_f32_16x16x32_bf16 v[100:103], v[170:173], v[212:215], v[100:103]
	v_mfma_f32_16x16x32_bf16 v[96:99], v[178:181], v[212:215], v[96:99]
	v_mfma_f32_16x16x32_bf16 v[84:87], v[170:173], v[238:241], v[84:87]
	v_mfma_f32_16x16x32_bf16 v[80:83], v[178:181], v[238:241], v[80:83]
	v_mfma_f32_16x16x32_bf16 v[132:135], v[174:177], v[200:203], v[132:135]
	v_mfma_f32_16x16x32_bf16 v[128:131], v[182:185], v[200:203], v[128:131]
	v_mfma_f32_16x16x32_bf16 v[116:119], v[174:177], v[208:211], v[116:119]
	v_mfma_f32_16x16x32_bf16 v[112:115], v[182:185], v[208:211], v[112:115]
	v_mfma_f32_16x16x32_bf16 v[100:103], v[174:177], v[234:237], v[100:103]
	v_mfma_f32_16x16x32_bf16 v[96:99], v[182:185], v[234:237], v[96:99]
	v_mfma_f32_16x16x32_bf16 v[84:87], v[174:177], v[242:245], v[84:87]
	v_mfma_f32_16x16x32_bf16 v[80:83], v[182:185], v[242:245], v[80:83]
	s_setprio 0
	s_barrier
; #define PG8_STAGE(bufoff, gbase, voff) do { _Pragma("unroll") for (int _i = 0; _i < 2; ++_i) \
;         __builtin_amdgcn_global_load_lds((const unsigned*)((const char*)(gbase) + (voff)[_i]), (PG8_LAS unsigned*)(lds + (bufoff) + ldsw + _i * 8192), 16, 0, 0); } while (0)
; #define PG8_LDA(dst, b, h) do { _Pragma("unroll") for (int m = 0; m < 4; ++m) _Pragma("unroll") for (int k = 0; k < 2; ++k) dst[m][k] = *(const PG8_LAS bf16x8*)(lds + PG8_SA(b, h) + aoff + m * 2048 + k * 1024); } while (0)
; #define PG8_BAR __builtin_amdgcn_s_barrier()
; template <class Epi, class Sched, bool ALIGN_EPI = false, bool SP2 = false>
; __device__ __forceinline__ void gemm_phase(PG8_LAS unsigned char* lds, const Gemm g, const Sched& S, const Epi& E, const int tid_in) {
;     ...
;             PG8_LDA(At, 1, 1); PG8_STAGE(PG8_SB(1, 0), b3, voffB); PG8_STAGE(PG8_SB(1, 1), b3 + hstep, voffB); PG8_STAGE(PG8_SA(1, 0), a3, voffA);
;             PG8_WAIT_V(8); PG8_WAIT_L(0); PG8_BAR; PG8_MMA(1, 0, At, B0); PG8_MMA(1, 1, At, B1); PG8_BAR; PG8_SCHED;
;             } else {
;             PG8_LDB(B0, 0, 0); PG8_SCHED; PG8_LDA(At, 0, 0); PG8_STAGE(PG8_SA(1, 1), a1 + hstep, voffA);
;             PG8_WAIT_L(8); PG8_BAR; PG8_WAIT_L(0); PG8_MMA(0, 0, At, B0); PG8_BAR; PG8_SCHED;
;             PG8_LDB(B1, 0, 1); PG8_STAGE(PG8_SB(0, 0), b2, voffB);
;             PG8_BAR; PG8_WAIT_L(0); PG8_MMA(0, 1, At, B1); PG8_BAR;
;             PG8_LDA(At, 0, 1); PG8_STAGE(PG8_SA(0, 0), a2, voffA);
;             PG8_BAR; PG8_WAIT_L(0); PG8_MMA(1, 0, At, B0); PG8_BAR; PG8_SCHED;
;             PG8_STAGE(PG8_SB(0, 1), b2 + hstep, voffB);
;             PG8_WAIT_V(6); PG8_BAR; PG8_MMA(1, 1, At, B1); PG8_BAR;
;             PG8_LDB(B0, 1, 0); PG8_SCHED; PG8_LDA(At, 1, 0); PG8_STAGE(PG8_SA(0, 1), a2 + hstep, voffA);
;             PG8_WAIT_L(8); PG8_BAR; PG8_WAIT_L(0); PG8_MMA(0, 0, At, B0); PG8_BAR; PG8_SCHED;
;             PG8_LDB(B1, 1, 1); PG8_STAGE(PG8_SB(1, 0), b3, voffB);
;             PG8_BAR; PG8_WAIT_L(0); PG8_MMA(0, 1, At, B1); PG8_BAR;
;             PG8_LDA(At, 1, 1); PG8_STAGE(PG8_SA(1, 0), a3, voffA);
;             PG8_BAR; PG8_WAIT_L(0); PG8_MMA(1, 0, At, B0); PG8_BAR; PG8_SCHED;
;             PG8_STAGE(PG8_SB(1, 1), b3 + hstep, voffB);
;             PG8_WAIT_V(6); PG8_BAR; PG8_MMA(1, 1, At, B1); PG8_BAR;
;             }
;         }
;         if constexpr (ALIGN_EPI) { if (wr == 0) PG8_BAR; }
	s_add_i32 s12, s61, s41
	v_lshl_add_u64 v[160:161], v[160:161], 0, s[92:93]
	s_mov_b32 m0, s12
	ds_read_b128 v[186:189], v168 offset:49152
	ds_read_b128 v[200:203], v168 offset:50176
	ds_read_b128 v[204:207], v168 offset:51200
	ds_read_b128 v[208:211], v168 offset:52224
	ds_read_b128 v[212:215], v168 offset:53248
	ds_read_b128 v[234:237], v168 offset:54272
	ds_read_b128 v[238:241], v168 offset:55296
	ds_read_b128 v[242:245], v168 offset:56320
	global_load_lds_dwordx4 v[160:161], off
	s_add_i32 m0, s12, 0x2000
	s_add_u32 s10, s10, 0x40080
	v_lshl_add_u64 v[160:161], v[190:191], 0, s[92:93]
	s_addc_u32 s11, s11, 0
	s_add_i32 s12, s62, s41
	global_load_lds_dwordx4 v[160:161], off
	v_lshl_add_u64 v[160:161], s[10:11], 0, v[148:149]
	s_mov_b32 m0, s12
	s_nop 0
	global_load_lds_dwordx4 v[160:161], off
	v_lshl_add_u64 v[160:161], s[10:11], 0, v[144:145]
	s_add_i32 m0, s12, 0x2000
	s_nop 0
	global_load_lds_dwordx4 v[160:161], off
	v_lshl_add_u64 v[160:161], v[218:219], 0, s[92:93]
	s_mov_b32 m0, s54
	s_nop 0
	global_load_lds_dwordx4 v[160:161], off
	v_lshl_add_u64 v[160:161], v[220:221], 0, s[92:93]
	s_mov_b32 m0, s55
	s_nop 0
	global_load_lds_dwordx4 v[160:161], off
	s_waitcnt vmcnt(8)
	s_waitcnt lgkmcnt(0)
	s_barrier
	s_setprio 1
	s_waitcnt lgkmcnt(0)
	v_mfma_f32_16x16x32_bf16 v[72:75], v[56:59], v[186:189], v[72:75]
	v_mfma_f32_16x16x32_bf16 v[60:63], v[68:71], v[186:189], v[60:63]
	v_mfma_f32_16x16x32_bf16 v[44:47], v[56:59], v[204:207], v[44:47]
	v_mfma_f32_16x16x32_bf16 v[40:43], v[68:71], v[204:207], v[40:43]
	v_mfma_f32_16x16x32_bf16 v[28:31], v[56:59], v[212:215], v[28:31]
	v_mfma_f32_16x16x32_bf16 v[24:27], v[68:71], v[212:215], v[24:27]
	v_mfma_f32_16x16x32_bf16 v[12:15], v[56:59], v[238:241], v[12:15]
	v_mfma_f32_16x16x32_bf16 v[8:11], v[68:71], v[238:241], v[8:11]
	v_mfma_f32_16x16x32_bf16 v[72:75], v[64:67], v[200:203], v[72:75]
	v_mfma_f32_16x16x32_bf16 v[60:63], v[76:79], v[200:203], v[60:63]
	v_mfma_f32_16x16x32_bf16 v[44:47], v[64:67], v[208:211], v[44:47]
	v_mfma_f32_16x16x32_bf16 v[40:43], v[76:79], v[208:211], v[40:43]
	v_mfma_f32_16x16x32_bf16 v[28:31], v[64:67], v[234:237], v[28:31]
	v_mfma_f32_16x16x32_bf16 v[24:27], v[76:79], v[234:237], v[24:27]
	v_mfma_f32_16x16x32_bf16 v[12:15], v[64:67], v[242:245], v[12:15]
	v_mfma_f32_16x16x32_bf16 v[8:11], v[76:79], v[242:245], v[8:11]
	s_setprio 0
	s_setprio 1
	v_mfma_f32_16x16x32_bf16 v[52:55], v[170:173], v[186:189], v[52:55]
	v_mfma_f32_16x16x32_bf16 v[48:51], v[178:181], v[186:189], v[48:51]
	v_mfma_f32_16x16x32_bf16 v[36:39], v[170:173], v[204:207], v[36:39]
	v_mfma_f32_16x16x32_bf16 v[32:35], v[178:181], v[204:207], v[32:35]
	v_mfma_f32_16x16x32_bf16 v[20:23], v[170:173], v[212:215], v[20:23]
	v_mfma_f32_16x16x32_bf16 v[16:19], v[178:181], v[212:215], v[16:19]
	v_mfma_f32_16x16x32_bf16 v[4:7], v[170:173], v[238:241], v[4:7]
	v_mfma_f32_16x16x32_bf16 v[0:3], v[178:181], v[238:241], v[0:3]
	v_mfma_f32_16x16x32_bf16 v[52:55], v[174:177], v[200:203], v[52:55]
	v_mfma_f32_16x16x32_bf16 v[48:51], v[182:185], v[200:203], v[48:51]
	v_mfma_f32_16x16x32_bf16 v[36:39], v[174:177], v[208:211], v[36:39]
	v_mfma_f32_16x16x32_bf16 v[32:35], v[182:185], v[208:211], v[32:35]
	v_mfma_f32_16x16x32_bf16 v[20:23], v[174:177], v[234:237], v[20:23]
	v_mfma_f32_16x16x32_bf16 v[16:19], v[182:185], v[234:237], v[16:19]
	v_mfma_f32_16x16x32_bf16 v[4:7], v[174:177], v[242:245], v[4:7]
	v_mfma_f32_16x16x32_bf16 v[0:3], v[182:185], v[242:245], v[0:3]
	s_setprio 0
	s_barrier
	s_add_i32 s60, s60, 2
	s_add_u32 s4, s4, 0x100
	s_addc_u32 s5, s5, 0
	s_add_u32 s58, s58, 0x100
	s_addc_u32 s59, s59, 0
	s_cmp_gt_u32 s60, 13
	s_cbranch_scc0 .LBB0_42
	s_and_b64 vcc, exec, s[34:35]
	s_cbranch_vccz .LBB0_45
	s_barrier

; #define PG8_STAGE(bufoff, gbase, voff) do { _Pragma("unroll") for (int _i = 0; _i < 2; ++_i) \
;         __builtin_amdgcn_global_load_lds((const unsigned*)((const char*)(gbase) + (voff)[_i]), (PG8_LAS unsigned*)(lds + (bufoff) + ldsw + _i * 8192), 16, 0, 0); } while (0)
; #define PG8_LDA(dst, b, h) do { _Pragma("unroll") for (int m = 0; m < 4; ++m) _Pragma("unroll") for (int k = 0; k < 2; ++k) dst[m][k] = *(const PG8_LAS bf16x8*)(lds + PG8_SA(b, h) + aoff + m * 2048 + k * 1024); } while (0)
; #define PG8_LDB(dst, b, h) do { _Pragma("unroll") for (int n = 0; n < 2; ++n) _Pragma("unroll") for (int k = 0; k < 2; ++k) dst[n][k] = *(const PG8_LAS bf16x8*)(lds + PG8_SB(b, h) + boff + n * 2048 + k * 1024); } while (0)
; #define PG8_MMA(ai, bj, At, Bt) do { __builtin_amdgcn_s_setprio(1); _Pragma("unroll") for (int m = 0; m < 4; ++m) _Pragma("unroll") for (int n = 0; n < 2; ++n) _Pragma("unroll") for (int k = 0; k < 2; ++k) \
;         acc[ai][bj][m][n] = __builtin_amdgcn_mfma_f32_16x16x32_bf16(Bt[n][k], At[m][k], acc[ai][bj][m][n], 0, 0, 0); __builtin_amdgcn_s_setprio(0); } while (0)
; #define PG8_WAIT_V(n) asm volatile("s_waitcnt vmcnt(" #n ")" ::: "memory")
; #define PG8_BAR __builtin_amdgcn_s_barrier()
; template <class Epi, class Sched, bool ALIGN_EPI = false, bool SP2 = false>
; __device__ __forceinline__ void gemm_phase(PG8_LAS unsigned char* lds, const Gemm g, const Sched& S, const Epi& E, const int tid_in) {
;     ...
;         for (int t = 0; t < nt; t += 2) {
;             const bool last = (t == nt - 2);
;             const char* a1 = cA + (size_t)(t + 1) * kstep;
;             const char* a2 = last ? nA : cA + (size_t)(t + 2) * kstep; const char* b2 = last ? nB : cB + (size_t)(t + 2) * kstep;
;             const char* a3 = a2 + kstep; const char* b3 = b2 + kstep;
;             if (last && has_next) S.a_ready(nxt);
;             if constexpr (SP2) {
;             PG8_LDB(B0, 0, 0); PG8_LDB(B1, 0, 1); PG8_SCHED; PG8_LDA(At, 0, 0); PG8_STAGE(PG8_SA(1, 1), a1 + hstep, voffA);
;             PG8_WAIT_V(8); PG8_WAIT_L(0); PG8_BAR; PG8_MMA(0, 0, At, B0); PG8_MMA(0, 1, At, B1); PG8_BAR; PG8_SCHED;
;             PG8_LDA(At, 0, 1); PG8_STAGE(PG8_SB(0, 0), b2, voffB); PG8_STAGE(PG8_SB(0, 1), b2 + hstep, voffB); PG8_STAGE(PG8_SA(0, 0), a2, voffA);
;             PG8_WAIT_V(8); PG8_WAIT_L(0); PG8_BAR; PG8_MMA(1, 0, At, B0); PG8_MMA(1, 1, At, B1); PG8_BAR; PG8_SCHED;
.LBB0_284:
	s_add_i32 s52, s26, 2
	s_add_u32 s53, s24, 0x80
	s_addc_u32 s27, s25, 0
	s_add_i32 s56, 0, 0x10000
	s_cmp_eq_u32 s28, s26
	s_cselect_b32 s27, s21, s27
	s_cselect_b32 s26, s20, s53
	s_cselect_b32 s55, s23, s51
	s_cselect_b32 s54, s22, s29
	s_add_i32 s53, 0, 0x14000
	v_add_u32_e32 v154, s56, v143
	v_add_u32_e32 v170, s53, v143
	ds_read_b128 v[138:141], v154
	ds_read_b128 v[146:149], v154 offset:1024
	ds_read_b128 v[150:153], v154 offset:2048
	ds_read_b128 v[154:157], v154 offset:3072
	ds_read_b128 v[158:161], v170
	ds_read_b128 v[162:165], v170 offset:1024
	ds_read_b128 v[166:169], v170 offset:2048
	ds_read_b128 v[170:173], v170 offset:3072
	v_lshl_add_u64 v[190:191], s[24:25], 0, v[134:135]
	s_add_i32 m0, s38, 0xc000
	ds_read_b128 v[174:177], v145
	ds_read_b128 v[178:181], v145 offset:1024
	ds_read_b128 v[182:185], v145 offset:2048
	ds_read_b128 v[186:189], v145 offset:3072
	ds_read_b128 v[200:203], v145 offset:4096
	ds_read_b128 v[204:207], v145 offset:5120
	ds_read_b128 v[208:211], v145 offset:6144
	ds_read_b128 v[212:215], v145 offset:7168
	global_load_lds_dwordx4 v[190:191], off
	v_lshl_add_u64 v[190:191], s[24:25], 0, v[136:137]
	s_add_i32 m0, s38, 0xe000
	s_nop 0
	global_load_lds_dwordx4 v[190:191], off
	s_waitcnt vmcnt(8)
	s_waitcnt lgkmcnt(0)
	s_barrier
	s_setprio 1
	s_waitcnt lgkmcnt(0)
	s_nop 0
	v_mfma_f32_16x16x32_bf16 v[124:127], v[138:141], v[174:177], v[124:127]
	v_mfma_f32_16x16x32_bf16 v[120:123], v[150:153], v[174:177], v[120:123]
	v_mfma_f32_16x16x32_bf16 v[108:111], v[138:141], v[182:185], v[108:111]
	v_mfma_f32_16x16x32_bf16 v[104:107], v[150:153], v[182:185], v[104:107]
	v_mfma_f32_16x16x32_bf16 v[92:95], v[138:141], v[200:203], v[92:95]
	v_mfma_f32_16x16x32_bf16 v[88:91], v[150:153], v[200:203], v[88:91]
	v_mfma_f32_16x16x32_bf16 v[76:79], v[138:141], v[208:211], v[76:79]
	v_mfma_f32_16x16x32_bf16 v[72:75], v[150:153], v[208:211], v[72:75]
	v_mfma_f32_16x16x32_bf16 v[124:127], v[146:149], v[178:181], v[124:127]
	v_mfma_f32_16x16x32_bf16 v[120:123], v[154:157], v[178:181], v[120:123]
	v_mfma_f32_16x16x32_bf16 v[108:111], v[146:149], v[186:189], v[108:111]
	v_mfma_f32_16x16x32_bf16 v[104:107], v[154:157], v[186:189], v[104:107]
	v_mfma_f32_16x16x32_bf16 v[92:95], v[146:149], v[204:207], v[92:95]
	v_mfma_f32_16x16x32_bf16 v[88:91], v[154:157], v[204:207], v[88:91]
	v_mfma_f32_16x16x32_bf16 v[76:79], v[146:149], v[212:215], v[76:79]
	v_mfma_f32_16x16x32_bf16 v[72:75], v[154:157], v[212:215], v[72:75]
	s_setprio 0
	s_setprio 1
	v_mfma_f32_16x16x32_bf16 v[116:119], v[158:161], v[174:177], v[116:119]
	v_mfma_f32_16x16x32_bf16 v[112:115], v[166:169], v[174:177], v[112:115]
	v_mfma_f32_16x16x32_bf16 v[100:103], v[158:161], v[182:185], v[100:103]
	v_mfma_f32_16x16x32_bf16 v[96:99], v[166:169], v[182:185], v[96:99]
	v_mfma_f32_16x16x32_bf16 v[84:87], v[158:161], v[200:203], v[84:87]
	v_mfma_f32_16x16x32_bf16 v[80:83], v[166:169], v[200:203], v[80:83]
	v_mfma_f32_16x16x32_bf16 v[68:71], v[158:161], v[208:211], v[68:71]
	v_mfma_f32_16x16x32_bf16 v[64:67], v[166:169], v[208:211], v[64:67]
	v_mfma_f32_16x16x32_bf16 v[116:119], v[162:165], v[178:181], v[116:119]
	v_mfma_f32_16x16x32_bf16 v[112:115], v[170:173], v[178:181], v[112:115]
	v_mfma_f32_16x16x32_bf16 v[100:103], v[162:165], v[186:189], v[100:103]
	v_mfma_f32_16x16x32_bf16 v[96:99], v[170:173], v[186:189], v[96:99]
	v_mfma_f32_16x16x32_bf16 v[84:87], v[162:165], v[204:207], v[84:87]
	v_mfma_f32_16x16x32_bf16 v[80:83], v[170:173], v[204:207], v[80:83]
	v_mfma_f32_16x16x32_bf16 v[68:71], v[162:165], v[212:215], v[68:71]
	v_mfma_f32_16x16x32_bf16 v[64:67], v[170:173], v[212:215], v[64:67]
	s_setprio 0
	s_barrier
	s_add_i32 s56, s56, s35
	v_lshl_add_u64 v[190:191], s[54:55], 0, v[192:193]
	s_mov_b32 m0, s56
	ds_read_b128 v[174:177], v145 offset:16384
	ds_read_b128 v[178:181], v145 offset:17408
	ds_read_b128 v[182:185], v145 offset:18432
	ds_read_b128 v[186:189], v145 offset:19456
	ds_read_b128 v[200:203], v145 offset:20480
	ds_read_b128 v[204:207], v145 offset:21504
	ds_read_b128 v[208:211], v145 offset:22528
	ds_read_b128 v[212:215], v145 offset:23552
	global_load_lds_dwordx4 v[190:191], off
	s_add_i32 m0, s56, 0x2000
	v_lshl_add_u64 v[218:219], s[54:55], 0, v[132:133]
	s_add_u32 s54, s54, s12
	s_addc_u32 s55, s55, 0
	s_add_i32 s53, s53, s35
	global_load_lds_dwordx4 v[218:219], off
	v_lshl_add_u64 v[220:221], s[54:55], 0, v[192:193]
	s_mov_b32 m0, s53
	v_lshl_add_u64 v[230:231], s[54:55], 0, v[132:133]
	global_load_lds_dwordx4 v[220:221], off
	s_add_i32 m0, s53, 0x2000
	v_lshl_add_u64 v[232:233], s[26:27], 0, v[128:129]
	global_load_lds_dwordx4 v[230:231], off
	s_mov_b32 m0, s38
	v_lshl_add_u64 v[234:235], s[26:27], 0, v[130:131]
	global_load_lds_dwordx4 v[232:233], off
	s_mov_b32 m0, s39
	s_nop 0
	global_load_lds_dwordx4 v[234:235], off
	s_waitcnt vmcnt(8)
	s_waitcnt lgkmcnt(0)
	s_barrier
; #define PG8_STAGE(bufoff, gbase, voff) do { _Pragma("unroll") for (int _i = 0; _i < 2; ++_i) \
;         __builtin_amdgcn_global_load_lds((const unsigned*)((const char*)(gbase) + (voff)[_i]), (PG8_LAS unsigned*)(lds + (bufoff) + ldsw + _i * 8192), 16, 0, 0); } while (0)
; #define PG8_LDA(dst, b, h) do { _Pragma("unroll") for (int m = 0; m < 4; ++m) _Pragma("unroll") for (int k = 0; k < 2; ++k) dst[m][k] = *(const PG8_LAS bf16x8*)(lds + PG8_SA(b, h) + aoff + m * 2048 + k * 1024); } while (0)
; #define PG8_LDB(dst, b, h) do { _Pragma("unroll") for (int n = 0; n < 2; ++n) _Pragma("unroll") for (int k = 0; k < 2; ++k) dst[n][k] = *(const PG8_LAS bf16x8*)(lds + PG8_SB(b, h) + boff + n * 2048 + k * 1024); } while (0)
; #define PG8_MMA(ai, bj, At, Bt) do { __builtin_amdgcn_s_setprio(1); _Pragma("unroll") for (int m = 0; m < 4; ++m) _Pragma("unroll") for (int n = 0; n < 2; ++n) _Pragma("unroll") for (int k = 0; k < 2; ++k) \
;         acc[ai][bj][m][n] = __builtin_amdgcn_mfma_f32_16x16x32_bf16(Bt[n][k], At[m][k], acc[ai][bj][m][n], 0, 0, 0); __builtin_amdgcn_s_setprio(0); } while (0)
; #define PG8_WAIT_V(n) asm volatile("s_waitcnt vmcnt(" #n ")" ::: "memory")
; #define PG8_WAIT_L(n) asm volatile("s_waitcnt lgkmcnt(" #n ")" ::: "memory")
; #define PG8_BAR __builtin_amdgcn_s_barrier()
; #define PG8_SCHED __builtin_amdgcn_sched_barrier(0)
; template <class Epi, class Sched, bool ALIGN_EPI = false, bool SP2 = false>
; __device__ __forceinline__ void gemm_phase(PG8_LAS unsigned char* lds, const Gemm g, const Sched& S, const Epi& E, const int tid_in) {
;     ...
;             PG8_WAIT_V(8); PG8_WAIT_L(0); PG8_BAR; PG8_MMA(1, 0, At, B0); PG8_MMA(1, 1, At, B1); PG8_BAR; PG8_SCHED;
;             PG8_LDB(B0, 1, 0); PG8_LDB(B1, 1, 1); PG8_SCHED; PG8_LDA(At, 1, 0); PG8_STAGE(PG8_SA(0, 1), a2 + hstep, voffA);
;             PG8_WAIT_V(8); PG8_WAIT_L(0); PG8_BAR; PG8_MMA(0, 0, At, B0); PG8_MMA(0, 1, At, B1); PG8_BAR; PG8_SCHED;
;             PG8_LDA(At, 1, 1); PG8_STAGE(PG8_SB(1, 0), b3, voffB); PG8_STAGE(PG8_SB(1, 1), b3 + hstep, voffB); PG8_STAGE(PG8_SA(1, 0), a3, voffA);
	s_setprio 1
	s_waitcnt lgkmcnt(0)
	v_mfma_f32_16x16x32_bf16 v[60:63], v[138:141], v[174:177], v[60:63]
	v_mfma_f32_16x16x32_bf16 v[56:59], v[150:153], v[174:177], v[56:59]
	v_mfma_f32_16x16x32_bf16 v[44:47], v[138:141], v[182:185], v[44:47]
	v_mfma_f32_16x16x32_bf16 v[40:43], v[150:153], v[182:185], v[40:43]
	v_mfma_f32_16x16x32_bf16 v[28:31], v[138:141], v[200:203], v[28:31]
	v_mfma_f32_16x16x32_bf16 v[24:27], v[150:153], v[200:203], v[24:27]
	v_mfma_f32_16x16x32_bf16 v[12:15], v[138:141], v[208:211], v[12:15]
	v_mfma_f32_16x16x32_bf16 v[8:11], v[150:153], v[208:211], v[8:11]
	v_mfma_f32_16x16x32_bf16 v[60:63], v[146:149], v[178:181], v[60:63]
	v_mfma_f32_16x16x32_bf16 v[56:59], v[154:157], v[178:181], v[56:59]
	v_mfma_f32_16x16x32_bf16 v[44:47], v[146:149], v[186:189], v[44:47]
	v_mfma_f32_16x16x32_bf16 v[40:43], v[154:157], v[186:189], v[40:43]
	v_mfma_f32_16x16x32_bf16 v[28:31], v[146:149], v[204:207], v[28:31]
	v_mfma_f32_16x16x32_bf16 v[24:27], v[154:157], v[204:207], v[24:27]
	v_mfma_f32_16x16x32_bf16 v[12:15], v[146:149], v[212:215], v[12:15]
	v_mfma_f32_16x16x32_bf16 v[8:11], v[154:157], v[212:215], v[8:11]
	s_setprio 0
	s_setprio 1
	v_mfma_f32_16x16x32_bf16 v[52:55], v[158:161], v[174:177], v[52:55]
	v_mfma_f32_16x16x32_bf16 v[48:51], v[166:169], v[174:177], v[48:51]
	v_mfma_f32_16x16x32_bf16 v[36:39], v[158:161], v[182:185], v[36:39]
	v_mfma_f32_16x16x32_bf16 v[32:35], v[166:169], v[182:185], v[32:35]
	v_mfma_f32_16x16x32_bf16 v[20:23], v[158:161], v[200:203], v[20:23]
	v_mfma_f32_16x16x32_bf16 v[16:19], v[166:169], v[200:203], v[16:19]
	v_mfma_f32_16x16x32_bf16 v[4:7], v[158:161], v[208:211], v[4:7]
	v_mfma_f32_16x16x32_bf16 v[0:3], v[166:169], v[208:211], v[0:3]
	v_mfma_f32_16x16x32_bf16 v[52:55], v[162:165], v[178:181], v[52:55]
	v_mfma_f32_16x16x32_bf16 v[48:51], v[170:173], v[178:181], v[48:51]
	v_mfma_f32_16x16x32_bf16 v[36:39], v[162:165], v[186:189], v[36:39]
	v_mfma_f32_16x16x32_bf16 v[32:35], v[170:173], v[186:189], v[32:35]
	v_mfma_f32_16x16x32_bf16 v[20:23], v[162:165], v[204:207], v[20:23]
	v_mfma_f32_16x16x32_bf16 v[16:19], v[170:173], v[204:207], v[16:19]
	v_mfma_f32_16x16x32_bf16 v[4:7], v[162:165], v[212:215], v[4:7]
	v_mfma_f32_16x16x32_bf16 v[0:3], v[170:173], v[212:215], v[0:3]
	s_setprio 0
	s_barrier
	s_add_i32 s53, 0, 0x18000
	s_add_i32 s54, 0, 0x1c000
	v_add_u32_e32 v154, s53, v143
	v_add_u32_e32 v170, s54, v143
	ds_read_b128 v[138:141], v154
	ds_read_b128 v[146:149], v154 offset:1024
	ds_read_b128 v[150:153], v154 offset:2048
	ds_read_b128 v[154:157], v154 offset:3072
	ds_read_b128 v[158:161], v170
	ds_read_b128 v[162:165], v170 offset:1024
	ds_read_b128 v[166:169], v170 offset:2048
	ds_read_b128 v[170:173], v170 offset:3072
	s_add_u32 s26, s26, s12
	s_addc_u32 s27, s27, 0
	s_mov_b32 m0, s40
	v_lshl_add_u64 v[236:237], s[26:27], 0, v[128:129]
	ds_read_b128 v[174:177], v145 offset:32768
	ds_read_b128 v[178:181], v145 offset:33792
	ds_read_b128 v[182:185], v145 offset:34816
	ds_read_b128 v[186:189], v145 offset:35840
	ds_read_b128 v[200:203], v145 offset:36864
	ds_read_b128 v[204:207], v145 offset:37888
	ds_read_b128 v[208:211], v145 offset:38912
	ds_read_b128 v[212:215], v145 offset:39936
	global_load_lds_dwordx4 v[236:237], off
	v_lshl_add_u64 v[236:237], s[26:27], 0, v[130:131]
	s_mov_b32 m0, s41
	s_nop 0
	global_load_lds_dwordx4 v[236:237], off
	s_waitcnt vmcnt(8)
	s_waitcnt lgkmcnt(0)
	s_barrier
	s_setprio 1
	s_waitcnt lgkmcnt(0)
	v_mfma_f32_16x16x32_bf16 v[124:127], v[138:141], v[174:177], v[124:127]
	v_mfma_f32_16x16x32_bf16 v[120:123], v[150:153], v[174:177], v[120:123]
	v_mfma_f32_16x16x32_bf16 v[108:111], v[138:141], v[182:185], v[108:111]
	v_mfma_f32_16x16x32_bf16 v[104:107], v[150:153], v[182:185], v[104:107]
	v_mfma_f32_16x16x32_bf16 v[92:95], v[138:141], v[200:203], v[92:95]
	v_mfma_f32_16x16x32_bf16 v[88:91], v[150:153], v[200:203], v[88:91]
	v_mfma_f32_16x16x32_bf16 v[76:79], v[138:141], v[208:211], v[76:79]
	v_mfma_f32_16x16x32_bf16 v[72:75], v[150:153], v[208:211], v[72:75]
	v_mfma_f32_16x16x32_bf16 v[124:127], v[146:149], v[178:181], v[124:127]
	v_mfma_f32_16x16x32_bf16 v[120:123], v[154:157], v[178:181], v[120:123]
	v_mfma_f32_16x16x32_bf16 v[108:111], v[146:149], v[186:189], v[108:111]
	v_mfma_f32_16x16x32_bf16 v[104:107], v[154:157], v[186:189], v[104:107]
	v_mfma_f32_16x16x32_bf16 v[92:95], v[146:149], v[204:207], v[92:95]
	v_mfma_f32_16x16x32_bf16 v[88:91], v[154:157], v[204:207], v[88:91]
	v_mfma_f32_16x16x32_bf16 v[76:79], v[146:149], v[212:215], v[76:79]
	v_mfma_f32_16x16x32_bf16 v[72:75], v[154:157], v[212:215], v[72:75]
	s_setprio 0
	s_setprio 1
	v_mfma_f32_16x16x32_bf16 v[116:119], v[158:161], v[174:177], v[116:119]
	v_mfma_f32_16x16x32_bf16 v[112:115], v[166:169], v[174:177], v[112:115]
	v_mfma_f32_16x16x32_bf16 v[100:103], v[158:161], v[182:185], v[100:103]
	v_mfma_f32_16x16x32_bf16 v[96:99], v[166:169], v[182:185], v[96:99]
	v_mfma_f32_16x16x32_bf16 v[84:87], v[158:161], v[200:203], v[84:87]
	v_mfma_f32_16x16x32_bf16 v[80:83], v[166:169], v[200:203], v[80:83]
	v_mfma_f32_16x16x32_bf16 v[68:71], v[158:161], v[208:211], v[68:71]
	v_mfma_f32_16x16x32_bf16 v[64:67], v[166:169], v[208:211], v[64:67]
	v_mfma_f32_16x16x32_bf16 v[116:119], v[162:165], v[178:181], v[116:119]
	v_mfma_f32_16x16x32_bf16 v[112:115], v[170:173], v[178:181], v[112:115]
	v_mfma_f32_16x16x32_bf16 v[100:103], v[162:165], v[186:189], v[100:103]
	v_mfma_f32_16x16x32_bf16 v[96:99], v[170:173], v[186:189], v[96:99]
	v_mfma_f32_16x16x32_bf16 v[84:87], v[162:165], v[204:207], v[84:87]
	v_mfma_f32_16x16x32_bf16 v[80:83], v[170:173], v[204:207], v[80:83]
	v_mfma_f32_16x16x32_bf16 v[68:71], v[162:165], v[212:215], v[68:71]
	v_mfma_f32_16x16x32_bf16 v[64:67], v[170:173], v[212:215], v[64:67]
	s_setprio 0
	s_barrier
; #define PG8_STAGE(bufoff, gbase, voff) do { _Pragma("unroll") for (int _i = 0; _i < 2; ++_i) \
;         __builtin_amdgcn_global_load_lds((const unsigned*)((const char*)(gbase) + (voff)[_i]), (PG8_LAS unsigned*)(lds + (bufoff) + ldsw + _i * 8192), 16, 0, 0); } while (0)
; #define PG8_LDA(dst, b, h) do { _Pragma("unroll") for (int m = 0; m < 4; ++m) _Pragma("unroll") for (int k = 0; k < 2; ++k) dst[m][k] = *(const PG8_LAS bf16x8*)(lds + PG8_SA(b, h) + aoff + m * 2048 + k * 1024); } while (0)
; #define PG8_BAR __builtin_amdgcn_s_barrier()
; template <class Epi, class Sched, bool ALIGN_EPI = false, bool SP2 = false>
; __device__ __forceinline__ void gemm_phase(PG8_LAS unsigned char* lds, const Gemm g, const Sched& S, const Epi& E, const int tid_in) {
;     ...
;             PG8_LDA(At, 1, 1); PG8_STAGE(PG8_SB(1, 0), b3, voffB); PG8_STAGE(PG8_SB(1, 1), b3 + hstep, voffB); PG8_STAGE(PG8_SA(1, 0), a3, voffA);
;             PG8_WAIT_V(8); PG8_WAIT_L(0); PG8_BAR; PG8_MMA(1, 0, At, B0); PG8_MMA(1, 1, At, B1); PG8_BAR; PG8_SCHED;
;             } else {
;             PG8_LDB(B0, 0, 0); PG8_SCHED; PG8_LDA(At, 0, 0); PG8_STAGE(PG8_SA(1, 1), a1 + hstep, voffA);
;             PG8_WAIT_L(8); PG8_BAR; PG8_WAIT_L(0); PG8_MMA(0, 0, At, B0); PG8_BAR; PG8_SCHED;
;             PG8_LDB(B1, 0, 1); PG8_STAGE(PG8_SB(0, 0), b2, voffB);
;             PG8_BAR; PG8_WAIT_L(0); PG8_MMA(0, 1, At, B1); PG8_BAR;
;             PG8_LDA(At, 0, 1); PG8_STAGE(PG8_SA(0, 0), a2, voffA);
;             PG8_BAR; PG8_WAIT_L(0); PG8_MMA(1, 0, At, B0); PG8_BAR; PG8_SCHED;
;             PG8_STAGE(PG8_SB(0, 1), b2 + hstep, voffB);
;             PG8_WAIT_V(6); PG8_BAR; PG8_MMA(1, 1, At, B1); PG8_BAR;
;             PG8_LDB(B0, 1, 0); PG8_SCHED; PG8_LDA(At, 1, 0); PG8_STAGE(PG8_SA(0, 1), a2 + hstep, voffA);
;             PG8_WAIT_L(8); PG8_BAR; PG8_WAIT_L(0); PG8_MMA(0, 0, At, B0); PG8_BAR; PG8_SCHED;
;             PG8_LDB(B1, 1, 1); PG8_STAGE(PG8_SB(1, 0), b3, voffB);
;             PG8_BAR; PG8_WAIT_L(0); PG8_MMA(0, 1, At, B1); PG8_BAR;
;             PG8_LDA(At, 1, 1); PG8_STAGE(PG8_SA(1, 0), a3, voffA);
;             PG8_BAR; PG8_WAIT_L(0); PG8_MMA(1, 0, At, B0); PG8_BAR; PG8_SCHED;
;             PG8_STAGE(PG8_SB(1, 1), b3 + hstep, voffB);
;             PG8_WAIT_V(6); PG8_BAR; PG8_MMA(1, 1, At, B1); PG8_BAR;
;             }
;         }
;         if constexpr (ALIGN_EPI) { if (wr == 0) PG8_BAR; }
	s_add_i32 s26, s53, s35
	v_lshl_add_u64 v[190:191], v[190:191], 0, s[92:93]
	s_mov_b32 m0, s26
	ds_read_b128 v[174:177], v145 offset:49152
	ds_read_b128 v[178:181], v145 offset:50176
	ds_read_b128 v[182:185], v145 offset:51200
	ds_read_b128 v[186:189], v145 offset:52224
	ds_read_b128 v[200:203], v145 offset:53248
	ds_read_b128 v[204:207], v145 offset:54272
	ds_read_b128 v[208:211], v145 offset:55296
	ds_read_b128 v[212:215], v145 offset:56320
	global_load_lds_dwordx4 v[190:191], off
	v_lshl_add_u64 v[190:191], v[218:219], 0, s[92:93]
	s_add_i32 m0, s26, 0x2000
	s_add_i32 s26, s54, s35
	global_load_lds_dwordx4 v[190:191], off
	v_lshl_add_u64 v[190:191], v[220:221], 0, s[92:93]
	s_mov_b32 m0, s26
	s_nop 0
	global_load_lds_dwordx4 v[190:191], off
	v_lshl_add_u64 v[190:191], v[230:231], 0, s[92:93]
	s_add_i32 m0, s26, 0x2000
	s_nop 0
	global_load_lds_dwordx4 v[190:191], off
	v_lshl_add_u64 v[190:191], v[232:233], 0, s[92:93]
	s_mov_b32 m0, s42
	s_nop 0
	global_load_lds_dwordx4 v[190:191], off
	v_lshl_add_u64 v[190:191], v[234:235], 0, s[92:93]
	s_mov_b32 m0, s43
	s_nop 0
	global_load_lds_dwordx4 v[190:191], off
	s_waitcnt vmcnt(8)
	s_waitcnt lgkmcnt(0)
	s_barrier
	s_setprio 1
	s_waitcnt lgkmcnt(0)
	s_nop 0
	v_mfma_f32_16x16x32_bf16 v[60:63], v[138:141], v[174:177], v[60:63]
	v_mfma_f32_16x16x32_bf16 v[56:59], v[150:153], v[174:177], v[56:59]
	v_mfma_f32_16x16x32_bf16 v[44:47], v[138:141], v[182:185], v[44:47]
	v_mfma_f32_16x16x32_bf16 v[40:43], v[150:153], v[182:185], v[40:43]
	v_mfma_f32_16x16x32_bf16 v[28:31], v[138:141], v[200:203], v[28:31]
	v_mfma_f32_16x16x32_bf16 v[24:27], v[150:153], v[200:203], v[24:27]
	v_mfma_f32_16x16x32_bf16 v[12:15], v[138:141], v[208:211], v[12:15]
	v_mfma_f32_16x16x32_bf16 v[8:11], v[150:153], v[208:211], v[8:11]
	v_mfma_f32_16x16x32_bf16 v[60:63], v[146:149], v[178:181], v[60:63]
	v_mfma_f32_16x16x32_bf16 v[56:59], v[154:157], v[178:181], v[56:59]
	v_mfma_f32_16x16x32_bf16 v[44:47], v[146:149], v[186:189], v[44:47]
	v_mfma_f32_16x16x32_bf16 v[40:43], v[154:157], v[186:189], v[40:43]
	v_mfma_f32_16x16x32_bf16 v[28:31], v[146:149], v[204:207], v[28:31]
	v_mfma_f32_16x16x32_bf16 v[24:27], v[154:157], v[204:207], v[24:27]
	v_mfma_f32_16x16x32_bf16 v[12:15], v[146:149], v[212:215], v[12:15]
	v_mfma_f32_16x16x32_bf16 v[8:11], v[154:157], v[212:215], v[8:11]
	s_setprio 0
	s_setprio 1
	v_mfma_f32_16x16x32_bf16 v[52:55], v[158:161], v[174:177], v[52:55]
	v_mfma_f32_16x16x32_bf16 v[48:51], v[166:169], v[174:177], v[48:51]
	v_mfma_f32_16x16x32_bf16 v[36:39], v[158:161], v[182:185], v[36:39]
	v_mfma_f32_16x16x32_bf16 v[32:35], v[166:169], v[182:185], v[32:35]
	v_mfma_f32_16x16x32_bf16 v[20:23], v[158:161], v[200:203], v[20:23]
	v_mfma_f32_16x16x32_bf16 v[16:19], v[166:169], v[200:203], v[16:19]
	v_mfma_f32_16x16x32_bf16 v[4:7], v[158:161], v[208:211], v[4:7]
	v_mfma_f32_16x16x32_bf16 v[0:3], v[166:169], v[208:211], v[0:3]
	v_mfma_f32_16x16x32_bf16 v[52:55], v[162:165], v[178:181], v[52:55]
	v_mfma_f32_16x16x32_bf16 v[48:51], v[170:173], v[178:181], v[48:51]
	v_mfma_f32_16x16x32_bf16 v[36:39], v[162:165], v[186:189], v[36:39]
	v_mfma_f32_16x16x32_bf16 v[32:35], v[170:173], v[186:189], v[32:35]
	v_mfma_f32_16x16x32_bf16 v[20:23], v[162:165], v[204:207], v[20:23]
	v_mfma_f32_16x16x32_bf16 v[16:19], v[170:173], v[204:207], v[16:19]
	v_mfma_f32_16x16x32_bf16 v[4:7], v[162:165], v[212:215], v[4:7]
	v_mfma_f32_16x16x32_bf16 v[0:3], v[170:173], v[212:215], v[0:3]
	s_setprio 0
	s_barrier
	s_add_u32 s24, s24, 0x100
	s_addc_u32 s25, s25, 0
	s_add_u32 s29, s29, 0x100
	s_addc_u32 s51, s51, 0
	s_cmp_ge_u32 s52, s50
	s_mov_b32 s26, s52
	s_cbranch_scc0 .LBB0_284
	s_and_b64 vcc, exec, s[16:17]
	s_cbranch_vccz .LBB0_287

; #define PG8_STAGE(bufoff, gbase, voff) do { _Pragma("unroll") for (int _i = 0; _i < 2; ++_i) \
;         __builtin_amdgcn_global_load_lds((const unsigned*)((const char*)(gbase) + (voff)[_i]), (PG8_LAS unsigned*)(lds + (bufoff) + ldsw + _i * 8192), 16, 0, 0); } while (0)
; #define PG8_LDA(dst, b, h) do { _Pragma("unroll") for (int m = 0; m < 4; ++m) _Pragma("unroll") for (int k = 0; k < 2; ++k) dst[m][k] = *(const PG8_LAS bf16x8*)(lds + PG8_SA(b, h) + aoff + m * 2048 + k * 1024); } while (0)
; #define PG8_LDB(dst, b, h) do { _Pragma("unroll") for (int n = 0; n < 2; ++n) _Pragma("unroll") for (int k = 0; k < 2; ++k) dst[n][k] = *(const PG8_LAS bf16x8*)(lds + PG8_SB(b, h) + boff + n * 2048 + k * 1024); } while (0)
; #define PG8_MMA(ai, bj, At, Bt) do { __builtin_amdgcn_s_setprio(1); _Pragma("unroll") for (int m = 0; m < 4; ++m) _Pragma("unroll") for (int n = 0; n < 2; ++n) _Pragma("unroll") for (int k = 0; k < 2; ++k) \
;         acc[ai][bj][m][n] = __builtin_amdgcn_mfma_f32_16x16x32_bf16(Bt[n][k], At[m][k], acc[ai][bj][m][n], 0, 0, 0); __builtin_amdgcn_s_setprio(0); } while (0)
; #define PG8_WAIT_V(n) asm volatile("s_waitcnt vmcnt(" #n ")" ::: "memory")
; #define PG8_BAR __builtin_amdgcn_s_barrier()
; template <class Epi, class Sched, bool ALIGN_EPI = false, bool SP2 = false>
; __device__ __forceinline__ void gemm_phase(PG8_LAS unsigned char* lds, const Gemm g, const Sched& S, const Epi& E, const int tid_in) {
;     ...
;         for (int t = 0; t < nt; t += 2) {
;             const bool last = (t == nt - 2);
;             const char* a1 = cA + (size_t)(t + 1) * kstep;
;             const char* a2 = last ? nA : cA + (size_t)(t + 2) * kstep; const char* b2 = last ? nB : cB + (size_t)(t + 2) * kstep;
;             const char* a3 = a2 + kstep; const char* b3 = b2 + kstep;
;             if (last && has_next) S.a_ready(nxt);
;             if constexpr (SP2) {
;             PG8_LDB(B0, 0, 0); PG8_LDB(B1, 0, 1); PG8_SCHED; PG8_LDA(At, 0, 0); PG8_STAGE(PG8_SA(1, 1), a1 + hstep, voffA);
;             PG8_WAIT_V(8); PG8_WAIT_L(0); PG8_BAR; PG8_MMA(0, 0, At, B0); PG8_MMA(0, 1, At, B1); PG8_BAR; PG8_SCHED;
;             PG8_LDA(At, 0, 1); PG8_STAGE(PG8_SB(0, 0), b2, voffB); PG8_STAGE(PG8_SB(0, 1), b2 + hstep, voffB); PG8_STAGE(PG8_SA(0, 0), a2, voffA);
;             PG8_WAIT_V(8); PG8_WAIT_L(0); PG8_BAR; PG8_MMA(1, 0, At, B0); PG8_MMA(1, 1, At, B1); PG8_BAR; PG8_SCHED;
.LBB0_307:
	s_add_u32 s20, s4, 0xfffc0080
	s_addc_u32 s21, s5, -1
	s_add_i32 s44, 0, 0x10000
	s_cmp_eq_u32 s43, 12
	s_cselect_b32 s23, s11, s21
	s_cselect_b32 s22, s39, s20
	s_cselect_b32 s21, s9, s42
	s_cselect_b32 s20, s40, s41
	s_add_i32 s46, 0, 0x14000
	v_add_u32_e32 v154, s44, v143
	v_add_u32_e32 v170, s46, v143
	ds_read_b128 v[138:141], v154
	ds_read_b128 v[146:149], v154 offset:1024
	ds_read_b128 v[150:153], v154 offset:2048
	ds_read_b128 v[154:157], v154 offset:3072
	ds_read_b128 v[158:161], v170
	ds_read_b128 v[162:165], v170 offset:1024
	ds_read_b128 v[166:169], v170 offset:2048
	ds_read_b128 v[170:173], v170 offset:3072
	s_add_i32 m0, s30, 0xc000
	ds_read_b128 v[174:177], v145
	ds_read_b128 v[178:181], v145 offset:1024
	ds_read_b128 v[182:185], v145 offset:2048
	ds_read_b128 v[186:189], v145 offset:3072
	ds_read_b128 v[200:203], v145 offset:4096
	ds_read_b128 v[204:207], v145 offset:5120
	ds_read_b128 v[208:211], v145 offset:6144
	ds_read_b128 v[212:215], v145 offset:7168
	global_load_lds_dwordx4 v134, s[4:5]
	s_add_i32 m0, s30, 0xe000
	s_nop 0
	global_load_lds_dwordx4 v136, s[4:5]
	s_waitcnt vmcnt(8)
	s_waitcnt lgkmcnt(0)
	s_barrier
	s_setprio 1
	s_waitcnt lgkmcnt(0)
	v_mfma_f32_16x16x32_bf16 v[124:127], v[138:141], v[174:177], v[124:127]
	v_mfma_f32_16x16x32_bf16 v[116:119], v[150:153], v[174:177], v[116:119]
	v_mfma_f32_16x16x32_bf16 v[108:111], v[138:141], v[182:185], v[108:111]
	v_mfma_f32_16x16x32_bf16 v[100:103], v[150:153], v[182:185], v[100:103]
	v_mfma_f32_16x16x32_bf16 v[92:95], v[138:141], v[200:203], v[92:95]
	v_mfma_f32_16x16x32_bf16 v[84:87], v[150:153], v[200:203], v[84:87]
	v_mfma_f32_16x16x32_bf16 v[76:79], v[138:141], v[208:211], v[76:79]
	v_mfma_f32_16x16x32_bf16 v[68:71], v[150:153], v[208:211], v[68:71]
	v_mfma_f32_16x16x32_bf16 v[124:127], v[146:149], v[178:181], v[124:127]
	v_mfma_f32_16x16x32_bf16 v[116:119], v[154:157], v[178:181], v[116:119]
	v_mfma_f32_16x16x32_bf16 v[108:111], v[146:149], v[186:189], v[108:111]
	v_mfma_f32_16x16x32_bf16 v[100:103], v[154:157], v[186:189], v[100:103]
	v_mfma_f32_16x16x32_bf16 v[92:95], v[146:149], v[204:207], v[92:95]
	v_mfma_f32_16x16x32_bf16 v[84:87], v[154:157], v[204:207], v[84:87]
	v_mfma_f32_16x16x32_bf16 v[76:79], v[146:149], v[212:215], v[76:79]
	v_mfma_f32_16x16x32_bf16 v[68:71], v[154:157], v[212:215], v[68:71]
	s_setprio 0
	s_setprio 1
	v_mfma_f32_16x16x32_bf16 v[120:123], v[158:161], v[174:177], v[120:123]
	v_mfma_f32_16x16x32_bf16 v[112:115], v[166:169], v[174:177], v[112:115]
	v_mfma_f32_16x16x32_bf16 v[104:107], v[158:161], v[182:185], v[104:107]
	v_mfma_f32_16x16x32_bf16 v[96:99], v[166:169], v[182:185], v[96:99]
	v_mfma_f32_16x16x32_bf16 v[88:91], v[158:161], v[200:203], v[88:91]
	v_mfma_f32_16x16x32_bf16 v[80:83], v[166:169], v[200:203], v[80:83]
	v_mfma_f32_16x16x32_bf16 v[72:75], v[158:161], v[208:211], v[72:75]
	v_mfma_f32_16x16x32_bf16 v[64:67], v[166:169], v[208:211], v[64:67]
	v_mfma_f32_16x16x32_bf16 v[120:123], v[162:165], v[178:181], v[120:123]
	v_mfma_f32_16x16x32_bf16 v[112:115], v[170:173], v[178:181], v[112:115]
	v_mfma_f32_16x16x32_bf16 v[104:107], v[162:165], v[186:189], v[104:107]
	v_mfma_f32_16x16x32_bf16 v[96:99], v[170:173], v[186:189], v[96:99]
	v_mfma_f32_16x16x32_bf16 v[88:91], v[162:165], v[204:207], v[88:91]
	v_mfma_f32_16x16x32_bf16 v[80:83], v[170:173], v[204:207], v[80:83]
	v_mfma_f32_16x16x32_bf16 v[72:75], v[162:165], v[212:215], v[72:75]
	v_mfma_f32_16x16x32_bf16 v[64:67], v[170:173], v[212:215], v[64:67]
	s_setprio 0
	s_barrier
	s_add_i32 s44, s44, s27
	s_mov_b32 m0, s44
	ds_read_b128 v[174:177], v145 offset:16384
	ds_read_b128 v[178:181], v145 offset:17408
	ds_read_b128 v[182:185], v145 offset:18432
	ds_read_b128 v[186:189], v145 offset:19456
	ds_read_b128 v[200:203], v145 offset:20480
	ds_read_b128 v[204:207], v145 offset:21504
	ds_read_b128 v[208:211], v145 offset:22528
	ds_read_b128 v[212:215], v145 offset:23552
	global_load_lds_dwordx4 v192, s[20:21]
	s_add_i32 m0, s44, 0x2000
	s_add_u32 s44, s20, 0x40000
	s_addc_u32 s45, s21, 0
	s_add_i32 s46, s46, s27
	global_load_lds_dwordx4 v128, s[20:21]
	s_mov_b32 m0, s46
	s_nop 0
	global_load_lds_dwordx4 v192, s[44:45]
	s_add_i32 m0, s46, 0x2000
	s_nop 0
	global_load_lds_dwordx4 v128, s[44:45]
	s_mov_b32 m0, s30
	s_nop 0
	global_load_lds_dwordx4 v132, s[22:23]
	s_mov_b32 m0, s31
	s_nop 0
	global_load_lds_dwordx4 v130, s[22:23]
	s_waitcnt vmcnt(8)
	s_waitcnt lgkmcnt(0)
	s_barrier
	s_setprio 1
	s_waitcnt lgkmcnt(0)
	v_mfma_f32_16x16x32_bf16 v[60:63], v[138:141], v[174:177], v[60:63]
	v_mfma_f32_16x16x32_bf16 v[52:55], v[150:153], v[174:177], v[52:55]
	v_mfma_f32_16x16x32_bf16 v[44:47], v[138:141], v[182:185], v[44:47]
	v_mfma_f32_16x16x32_bf16 v[36:39], v[150:153], v[182:185], v[36:39]
	v_mfma_f32_16x16x32_bf16 v[28:31], v[138:141], v[200:203], v[28:31]
	v_mfma_f32_16x16x32_bf16 v[20:23], v[150:153], v[200:203], v[20:23]
	v_mfma_f32_16x16x32_bf16 v[12:15], v[138:141], v[208:211], v[12:15]
	v_mfma_f32_16x16x32_bf16 v[4:7], v[150:153], v[208:211], v[4:7]
	v_mfma_f32_16x16x32_bf16 v[60:63], v[146:149], v[178:181], v[60:63]
	v_mfma_f32_16x16x32_bf16 v[52:55], v[154:157], v[178:181], v[52:55]
	v_mfma_f32_16x16x32_bf16 v[44:47], v[146:149], v[186:189], v[44:47]
	v_mfma_f32_16x16x32_bf16 v[36:39], v[154:157], v[186:189], v[36:39]
	v_mfma_f32_16x16x32_bf16 v[28:31], v[146:149], v[204:207], v[28:31]
	v_mfma_f32_16x16x32_bf16 v[20:23], v[154:157], v[204:207], v[20:23]
	v_mfma_f32_16x16x32_bf16 v[12:15], v[146:149], v[212:215], v[12:15]
	v_mfma_f32_16x16x32_bf16 v[4:7], v[154:157], v[212:215], v[4:7]
	s_setprio 0
	s_setprio 1
	v_mfma_f32_16x16x32_bf16 v[56:59], v[158:161], v[174:177], v[56:59]
	v_mfma_f32_16x16x32_bf16 v[48:51], v[166:169], v[174:177], v[48:51]
	v_mfma_f32_16x16x32_bf16 v[40:43], v[158:161], v[182:185], v[40:43]
	v_mfma_f32_16x16x32_bf16 v[32:35], v[166:169], v[182:185], v[32:35]
	v_mfma_f32_16x16x32_bf16 v[24:27], v[158:161], v[200:203], v[24:27]
	v_mfma_f32_16x16x32_bf16 v[16:19], v[166:169], v[200:203], v[16:19]
	v_mfma_f32_16x16x32_bf16 v[8:11], v[158:161], v[208:211], v[8:11]
	v_mfma_f32_16x16x32_bf16 v[0:3], v[166:169], v[208:211], v[0:3]
	v_mfma_f32_16x16x32_bf16 v[56:59], v[162:165], v[178:181], v[56:59]
	v_mfma_f32_16x16x32_bf16 v[48:51], v[170:173], v[178:181], v[48:51]
	v_mfma_f32_16x16x32_bf16 v[40:43], v[162:165], v[186:189], v[40:43]
	v_mfma_f32_16x16x32_bf16 v[32:35], v[170:173], v[186:189], v[32:35]
	v_mfma_f32_16x16x32_bf16 v[24:27], v[162:165], v[204:207], v[24:27]
	v_mfma_f32_16x16x32_bf16 v[16:19], v[170:173], v[204:207], v[16:19]
	v_mfma_f32_16x16x32_bf16 v[8:11], v[162:165], v[212:215], v[8:11]
	v_mfma_f32_16x16x32_bf16 v[0:3], v[170:173], v[212:215], v[0:3]
	s_setprio 0
	s_barrier
; #define PG8_STAGE(bufoff, gbase, voff) do { _Pragma("unroll") for (int _i = 0; _i < 2; ++_i) \
;         __builtin_amdgcn_global_load_lds((const unsigned*)((const char*)(gbase) + (voff)[_i]), (PG8_LAS unsigned*)(lds + (bufoff) + ldsw + _i * 8192), 16, 0, 0); } while (0)
; #define PG8_BAR __builtin_amdgcn_s_barrier()
; template <class Epi, class Sched, bool ALIGN_EPI = false, bool SP2 = false>
; __device__ __forceinline__ void gemm_phase(PG8_LAS unsigned char* lds, const Gemm g, const Sched& S, const Epi& E, const int tid_in) {
;     ...
;             PG8_LDB(B0, 1, 0); PG8_LDB(B1, 1, 1); PG8_SCHED; PG8_LDA(At, 1, 0); PG8_STAGE(PG8_SA(0, 1), a2 + hstep, voffA);
;             PG8_WAIT_V(8); PG8_WAIT_L(0); PG8_BAR; PG8_MMA(0, 0, At, B0); PG8_MMA(0, 1, At, B1); PG8_BAR; PG8_SCHED;
;             PG8_LDA(At, 1, 1); PG8_STAGE(PG8_SB(1, 0), b3, voffB); PG8_STAGE(PG8_SB(1, 1), b3 + hstep, voffB); PG8_STAGE(PG8_SA(1, 0), a3, voffA);
;             PG8_WAIT_V(8); PG8_WAIT_L(0); PG8_BAR; PG8_MMA(1, 0, At, B0); PG8_MMA(1, 1, At, B1); PG8_BAR; PG8_SCHED;
;             } else {
;             PG8_LDB(B0, 0, 0); PG8_SCHED; PG8_LDA(At, 0, 0); PG8_STAGE(PG8_SA(1, 1), a1 + hstep, voffA);
;             PG8_WAIT_L(8); PG8_BAR; PG8_WAIT_L(0); PG8_MMA(0, 0, At, B0); PG8_BAR; PG8_SCHED;
;             PG8_LDB(B1, 0, 1); PG8_STAGE(PG8_SB(0, 0), b2, voffB);
;             PG8_BAR; PG8_WAIT_L(0); PG8_MMA(0, 1, At, B1); PG8_BAR;
;             PG8_LDA(At, 0, 1); PG8_STAGE(PG8_SA(0, 0), a2, voffA);
;             PG8_BAR; PG8_WAIT_L(0); PG8_MMA(1, 0, At, B0); PG8_BAR; PG8_SCHED;
;             PG8_STAGE(PG8_SB(0, 1), b2 + hstep, voffB);
;             PG8_WAIT_V(6); PG8_BAR; PG8_MMA(1, 1, At, B1); PG8_BAR;
;             PG8_LDB(B0, 1, 0); PG8_SCHED; PG8_LDA(At, 1, 0); PG8_STAGE(PG8_SA(0, 1), a2 + hstep, voffA);
;             PG8_WAIT_L(8); PG8_BAR; PG8_WAIT_L(0); PG8_MMA(0, 0, At, B0); PG8_BAR; PG8_SCHED;
;             PG8_LDB(B1, 1, 1); PG8_STAGE(PG8_SB(1, 0), b3, voffB);
;             PG8_BAR; PG8_WAIT_L(0); PG8_MMA(0, 1, At, B1); PG8_BAR;
;             PG8_LDA(At, 1, 1); PG8_STAGE(PG8_SA(1, 0), a3, voffA);
;             PG8_BAR; PG8_WAIT_L(0); PG8_MMA(1, 0, At, B0); PG8_BAR; PG8_SCHED;
;             PG8_STAGE(PG8_SB(1, 1), b3 + hstep, voffB);
;             PG8_WAIT_V(6); PG8_BAR; PG8_MMA(1, 1, At, B1); PG8_BAR;
;             }
;         }
;         if constexpr (ALIGN_EPI) { if (wr == 0) PG8_BAR; }
	s_add_i32 s44, 0, 0x18000
	s_add_i32 s45, 0, 0x1c000
	v_add_u32_e32 v154, s44, v143
	v_add_u32_e32 v170, s45, v143
	ds_read_b128 v[138:141], v154
	ds_read_b128 v[146:149], v154 offset:1024
	ds_read_b128 v[150:153], v154 offset:2048
	ds_read_b128 v[154:157], v154 offset:3072
	ds_read_b128 v[158:161], v170
	ds_read_b128 v[162:165], v170 offset:1024
	ds_read_b128 v[166:169], v170 offset:2048
	ds_read_b128 v[170:173], v170 offset:3072
	s_add_u32 s22, s22, 0x40000
	s_addc_u32 s23, s23, 0
	s_mov_b32 m0, s34
	ds_read_b128 v[174:177], v145 offset:32768
	ds_read_b128 v[178:181], v145 offset:33792
	ds_read_b128 v[182:185], v145 offset:34816
	ds_read_b128 v[186:189], v145 offset:35840
	ds_read_b128 v[200:203], v145 offset:36864
	ds_read_b128 v[204:207], v145 offset:37888
	ds_read_b128 v[208:211], v145 offset:38912
	ds_read_b128 v[212:215], v145 offset:39936
	global_load_lds_dwordx4 v132, s[22:23]
	s_mov_b32 m0, s35
	s_nop 0
	global_load_lds_dwordx4 v130, s[22:23]
	s_waitcnt vmcnt(8)
	s_waitcnt lgkmcnt(0)
	s_barrier
	s_setprio 1
	s_waitcnt lgkmcnt(0)
	s_nop 0
	v_mfma_f32_16x16x32_bf16 v[124:127], v[138:141], v[174:177], v[124:127]
	v_mfma_f32_16x16x32_bf16 v[116:119], v[150:153], v[174:177], v[116:119]
	v_mfma_f32_16x16x32_bf16 v[108:111], v[138:141], v[182:185], v[108:111]
	v_mfma_f32_16x16x32_bf16 v[100:103], v[150:153], v[182:185], v[100:103]
	v_mfma_f32_16x16x32_bf16 v[92:95], v[138:141], v[200:203], v[92:95]
	v_mfma_f32_16x16x32_bf16 v[84:87], v[150:153], v[200:203], v[84:87]
	v_mfma_f32_16x16x32_bf16 v[76:79], v[138:141], v[208:211], v[76:79]
	v_mfma_f32_16x16x32_bf16 v[68:71], v[150:153], v[208:211], v[68:71]
	v_mfma_f32_16x16x32_bf16 v[124:127], v[146:149], v[178:181], v[124:127]
	v_mfma_f32_16x16x32_bf16 v[116:119], v[154:157], v[178:181], v[116:119]
	v_mfma_f32_16x16x32_bf16 v[108:111], v[146:149], v[186:189], v[108:111]
	v_mfma_f32_16x16x32_bf16 v[100:103], v[154:157], v[186:189], v[100:103]
	v_mfma_f32_16x16x32_bf16 v[92:95], v[146:149], v[204:207], v[92:95]
	v_mfma_f32_16x16x32_bf16 v[84:87], v[154:157], v[204:207], v[84:87]
	v_mfma_f32_16x16x32_bf16 v[76:79], v[146:149], v[212:215], v[76:79]
	v_mfma_f32_16x16x32_bf16 v[68:71], v[154:157], v[212:215], v[68:71]
	s_setprio 0
	s_setprio 1
	v_mfma_f32_16x16x32_bf16 v[120:123], v[158:161], v[174:177], v[120:123]
	v_mfma_f32_16x16x32_bf16 v[112:115], v[166:169], v[174:177], v[112:115]
	v_mfma_f32_16x16x32_bf16 v[104:107], v[158:161], v[182:185], v[104:107]
	v_mfma_f32_16x16x32_bf16 v[96:99], v[166:169], v[182:185], v[96:99]
	v_mfma_f32_16x16x32_bf16 v[88:91], v[158:161], v[200:203], v[88:91]
	v_mfma_f32_16x16x32_bf16 v[80:83], v[166:169], v[200:203], v[80:83]
	v_mfma_f32_16x16x32_bf16 v[72:75], v[158:161], v[208:211], v[72:75]
	v_mfma_f32_16x16x32_bf16 v[64:67], v[166:169], v[208:211], v[64:67]
	v_mfma_f32_16x16x32_bf16 v[120:123], v[162:165], v[178:181], v[120:123]
	v_mfma_f32_16x16x32_bf16 v[112:115], v[170:173], v[178:181], v[112:115]
	v_mfma_f32_16x16x32_bf16 v[104:107], v[162:165], v[186:189], v[104:107]
	v_mfma_f32_16x16x32_bf16 v[96:99], v[170:173], v[186:189], v[96:99]
	v_mfma_f32_16x16x32_bf16 v[88:91], v[162:165], v[204:207], v[88:91]
	v_mfma_f32_16x16x32_bf16 v[80:83], v[170:173], v[204:207], v[80:83]
	v_mfma_f32_16x16x32_bf16 v[72:75], v[162:165], v[212:215], v[72:75]
	v_mfma_f32_16x16x32_bf16 v[64:67], v[170:173], v[212:215], v[64:67]
	s_setprio 0
	s_barrier
	s_sub_u32 s22, s22, 0x3ff80
	s_subb_u32 s23, s23, 0
	s_add_u32 s20, s20, 0x80
	s_addc_u32 s21, s21, 0
	s_add_i32 s46, s44, s27
	s_mov_b32 m0, s46
	ds_read_b128 v[174:177], v145 offset:49152
	ds_read_b128 v[178:181], v145 offset:50176
	ds_read_b128 v[182:185], v145 offset:51200
	ds_read_b128 v[186:189], v145 offset:52224
	ds_read_b128 v[200:203], v145 offset:53248
	ds_read_b128 v[204:207], v145 offset:54272
	ds_read_b128 v[208:211], v145 offset:55296
	ds_read_b128 v[212:215], v145 offset:56320
	global_load_lds_dwordx4 v192, s[20:21]
	s_add_i32 m0, s46, 0x2000
	s_add_i32 s46, s45, s27
	global_load_lds_dwordx4 v128, s[20:21]
	s_add_u32 s20, s20, 0x40000
	s_addc_u32 s21, s21, 0
	s_mov_b32 m0, s46
	s_nop 0
	global_load_lds_dwordx4 v192, s[20:21]
	s_add_i32 m0, s46, 0x2000
	s_nop 0
	global_load_lds_dwordx4 v128, s[20:21]
	s_mov_b32 m0, s36
	s_nop 0
	global_load_lds_dwordx4 v132, s[22:23]
	s_mov_b32 m0, s37
	s_nop 0
	global_load_lds_dwordx4 v130, s[22:23]
	s_waitcnt vmcnt(8)
	s_waitcnt lgkmcnt(0)
	s_barrier
	s_setprio 1
	s_waitcnt lgkmcnt(0)
	v_mfma_f32_16x16x32_bf16 v[60:63], v[138:141], v[174:177], v[60:63]
	v_mfma_f32_16x16x32_bf16 v[52:55], v[150:153], v[174:177], v[52:55]
	v_mfma_f32_16x16x32_bf16 v[44:47], v[138:141], v[182:185], v[44:47]
	v_mfma_f32_16x16x32_bf16 v[36:39], v[150:153], v[182:185], v[36:39]
	v_mfma_f32_16x16x32_bf16 v[28:31], v[138:141], v[200:203], v[28:31]
	v_mfma_f32_16x16x32_bf16 v[20:23], v[150:153], v[200:203], v[20:23]
	v_mfma_f32_16x16x32_bf16 v[12:15], v[138:141], v[208:211], v[12:15]
	v_mfma_f32_16x16x32_bf16 v[4:7], v[150:153], v[208:211], v[4:7]
	v_mfma_f32_16x16x32_bf16 v[60:63], v[146:149], v[178:181], v[60:63]
	v_mfma_f32_16x16x32_bf16 v[52:55], v[154:157], v[178:181], v[52:55]
	v_mfma_f32_16x16x32_bf16 v[44:47], v[146:149], v[186:189], v[44:47]
	v_mfma_f32_16x16x32_bf16 v[36:39], v[154:157], v[186:189], v[36:39]
	v_mfma_f32_16x16x32_bf16 v[28:31], v[146:149], v[204:207], v[28:31]
	v_mfma_f32_16x16x32_bf16 v[20:23], v[154:157], v[204:207], v[20:23]
	v_mfma_f32_16x16x32_bf16 v[12:15], v[146:149], v[212:215], v[12:15]
	v_mfma_f32_16x16x32_bf16 v[4:7], v[154:157], v[212:215], v[4:7]
	s_setprio 0
	s_setprio 1
	v_mfma_f32_16x16x32_bf16 v[56:59], v[158:161], v[174:177], v[56:59]
	v_mfma_f32_16x16x32_bf16 v[48:51], v[166:169], v[174:177], v[48:51]
	v_mfma_f32_16x16x32_bf16 v[40:43], v[158:161], v[182:185], v[40:43]
	v_mfma_f32_16x16x32_bf16 v[32:35], v[166:169], v[182:185], v[32:35]
	v_mfma_f32_16x16x32_bf16 v[24:27], v[158:161], v[200:203], v[24:27]
	v_mfma_f32_16x16x32_bf16 v[16:19], v[166:169], v[200:203], v[16:19]
	v_mfma_f32_16x16x32_bf16 v[8:11], v[158:161], v[208:211], v[8:11]
	v_mfma_f32_16x16x32_bf16 v[0:3], v[166:169], v[208:211], v[0:3]
	v_mfma_f32_16x16x32_bf16 v[56:59], v[162:165], v[178:181], v[56:59]
	v_mfma_f32_16x16x32_bf16 v[48:51], v[170:173], v[178:181], v[48:51]
	v_mfma_f32_16x16x32_bf16 v[40:43], v[162:165], v[186:189], v[40:43]
	v_mfma_f32_16x16x32_bf16 v[32:35], v[170:173], v[186:189], v[32:35]
	v_mfma_f32_16x16x32_bf16 v[24:27], v[162:165], v[204:207], v[24:27]
	v_mfma_f32_16x16x32_bf16 v[16:19], v[170:173], v[204:207], v[16:19]
	v_mfma_f32_16x16x32_bf16 v[8:11], v[162:165], v[212:215], v[8:11]
	v_mfma_f32_16x16x32_bf16 v[0:3], v[170:173], v[212:215], v[0:3]
	s_setprio 0
	s_barrier
	s_add_i32 s43, s43, 2
	s_add_u32 s4, s4, 0x100
	s_addc_u32 s5, s5, 0
	s_add_u32 s41, s41, 0x100
	s_addc_u32 s42, s42, 0
	s_cmp_gt_u32 s43, 13
	s_cbranch_scc0 .LBB0_307
	s_and_b64 vcc, exec, s[18:19]
	s_cbranch_vccz .LBB0_310
	s_barrier
